# attention loop-control SALU moved into final P.V MFMA run, dead pointer increments dropped, row-max lane swap deferred to rescale path
# speedup vs baseline: 1.0101x; 1.0033x over previous
.LBB0_622:
	v_add3_u32 v165, s57, v143, v163
	ds_read_b128 v[190:193], v165 offset:18432
	ds_read_b128 v[194:197], v165 offset:18448
	ds_read_b128 v[128:131], v165 offset:23040
	ds_read_b128 v[132:135], v165 offset:23056
	ds_read_b128 v[136:139], v165 offset:27648
	ds_read_b128 v[166:169], v165 offset:27664
	ds_read_b128 v[170:173], v165 offset:32256
	ds_read_b128 v[178:181], v165 offset:32272
	v_exp_f32_e32 v96, v96
	v_exp_f32_e32 v97, v97
	v_exp_f32_e32 v98, v98
	v_exp_f32_e32 v99, v99
	v_exp_f32_e32 v100, v100
	v_add_f32_e32 v198, v97, v96
	v_exp_f32_e32 v101, v101
	v_add_f32_e32 v198, v98, v198
	v_exp_f32_e32 v102, v102
	v_add_f32_e32 v198, v99, v198
	v_exp_f32_e32 v103, v103
	v_add_f32_e32 v198, v100, v198
	v_exp_f32_e32 v104, v104
	v_add_f32_e32 v198, v101, v198
	v_exp_f32_e32 v105, v105
	v_add_f32_e32 v198, v102, v198
	v_exp_f32_e32 v106, v106
	v_add_f32_e32 v198, v103, v198
	v_exp_f32_e32 v107, v107
	v_add_f32_e32 v198, v104, v198
	v_exp_f32_e32 v108, v108
	v_add_f32_e32 v198, v105, v198
	v_exp_f32_e32 v109, v109
	v_add_f32_e32 v198, v106, v198
	v_exp_f32_e32 v110, v110
	v_add_f32_e32 v198, v107, v198
	v_exp_f32_e32 v111, v111
	v_add_f32_e32 v198, v108, v198
	v_add_f32_e32 v198, v109, v198
	v_add_f32_e32 v198, v110, v198
	v_add_f32_e32 v198, v111, v198
	v_add_f32_e32 v157, v157, v198
	v_cvt_pk_bf16_f32 v96, v96, v97
	v_cvt_pk_bf16_f32 v97, v98, v99
	v_cvt_pk_bf16_f32 v98, v100, v101
	v_cvt_pk_bf16_f32 v99, v102, v103
	v_cvt_pk_bf16_f32 v100, v104, v105
	v_cvt_pk_bf16_f32 v101, v106, v107
	v_cvt_pk_bf16_f32 v102, v108, v109
	v_cvt_pk_bf16_f32 v103, v110, v111
	s_waitcnt lgkmcnt(7)
	v_mfma_f32_32x32x16_bf16 v[48:63], v[190:193], v[96:99], v[48:63]
	v_exp_f32_e32 v174, v80
	v_exp_f32_e32 v175, v81
	v_exp_f32_e32 v182, v82
	v_exp_f32_e32 v183, v83
	v_add_f32_e32 v80, v175, v174
	v_add_f32_e32 v80, v182, v80
	s_waitcnt lgkmcnt(5)
	v_mfma_f32_32x32x16_bf16 v[0:15], v[128:131], v[96:99], v[0:15]
	v_add_f32_e32 v80, v183, v80
	v_mfma_f32_32x32x16_bf16 v[48:63], v[194:197], v[100:103], v[48:63]
	v_exp_f32_e32 v128, v84
	v_exp_f32_e32 v129, v85
	v_exp_f32_e32 v130, v86
	v_exp_f32_e32 v131, v87
	v_add_f32_e32 v80, v128, v80
	v_add_f32_e32 v80, v129, v80
	v_add_f32_e32 v80, v130, v80
	s_waitcnt lgkmcnt(4)
	v_mfma_f32_32x32x16_bf16 v[0:15], v[132:135], v[100:103], v[0:15]
	v_add_f32_e32 v184, v131, v80
	ds_read_b128 v[80:83], v165 offset:18496
	ds_read_b128 v[84:87], v165 offset:18512
	ds_read_b128 v[104:107], v165 offset:23104
	ds_read_b128 v[108:111], v165 offset:23120
	s_waitcnt lgkmcnt(7)
	v_mfma_f32_32x32x16_bf16 v[32:47], v[136:139], v[96:99], v[32:47]
	v_exp_f32_e32 v132, v88
	v_exp_f32_e32 v133, v89
	v_exp_f32_e32 v134, v90
	v_exp_f32_e32 v135, v91
	v_add_f32_e32 v88, v132, v184
	v_add_f32_e32 v88, v133, v88
	v_add_f32_e32 v88, v134, v88
	s_waitcnt lgkmcnt(5)
	v_mfma_f32_32x32x16_bf16 v[16:31], v[170:173], v[96:99], v[16:31]
	v_add_f32_e32 v88, v135, v88
	v_exp_f32_e32 v96, v92
	v_mfma_f32_32x32x16_bf16 v[32:47], v[166:169], v[100:103], v[32:47]
	v_exp_f32_e32 v97, v93
	v_exp_f32_e32 v98, v94
	v_exp_f32_e32 v95, v95
	v_add_f32_e32 v88, v96, v88
	v_add_f32_e32 v88, v97, v88
	v_add_f32_e32 v88, v98, v88
	v_add_f32_e32 v88, v95, v88
	s_waitcnt lgkmcnt(4)
	v_mfma_f32_32x32x16_bf16 v[16:31], v[178:181], v[100:103], v[16:31]
	v_add_f32_e32 v157, v157, v88
	v_cvt_pk_bf16_f32 v88, v174, v175
	v_cvt_pk_bf16_f32 v89, v182, v183
	v_cvt_pk_bf16_f32 v90, v128, v129
	v_cvt_pk_bf16_f32 v91, v130, v131
	v_cvt_pk_bf16_f32 v92, v132, v133
	v_cvt_pk_bf16_f32 v93, v134, v135
	v_cvt_pk_bf16_f32 v94, v96, v97
	v_cvt_pk_bf16_f32 v95, v98, v95
	ds_read_b128 v[96:99], v165 offset:27712
	ds_read_b128 v[100:103], v165 offset:27728
	ds_read_b128 v[128:131], v165 offset:32320
	ds_read_b128 v[132:135], v165 offset:32336
	s_waitcnt lgkmcnt(7)
	v_mfma_f32_32x32x16_bf16 v[48:63], v[80:83], v[88:91], v[48:63]
	s_waitcnt lgkmcnt(5)
	v_mfma_f32_32x32x16_bf16 v[0:15], v[104:107], v[88:91], v[0:15]
	s_add_i32 s4, s9, 0x9000
	s_cmp_lg_u32 s9, 0x12000
	s_cselect_b32 s9, s4, 0
	v_mfma_f32_32x32x16_bf16 v[48:63], v[84:87], v[92:95], v[48:63]
	s_waitcnt lgkmcnt(4)
	v_mfma_f32_32x32x16_bf16 v[0:15], v[108:111], v[92:95], v[0:15]
	s_add_i32 s4, s56, 1
	s_cmp_lg_u32 s56, 2
	s_cselect_b32 s56, s4, 0
	s_waitcnt lgkmcnt(3)
	v_mfma_f32_32x32x16_bf16 v[32:47], v[96:99], v[88:91], v[32:47]
	s_waitcnt lgkmcnt(1)
	v_mfma_f32_32x32x16_bf16 v[16:31], v[128:131], v[88:91], v[16:31]
	s_add_i32 s8, s8, 1
	s_add_i32 s87, s87, 64
	v_mfma_f32_32x32x16_bf16 v[32:47], v[100:103], v[92:95], v[32:47]
	s_waitcnt lgkmcnt(0)
	v_mfma_f32_32x32x16_bf16 v[16:31], v[132:135], v[92:95], v[16:31]
	s_cmpk_lg_i32 s87, 0xfc0
	s_waitcnt lgkmcnt(0)
	s_barrier
	s_cbranch_scc0 .LBB0_633

.LBB0_627:
	s_nop 10
	v_max3_f32 v128, v96, v97, v98
	v_max3_f32 v129, v80, v81, v82
	v_max3_f32 v128, v128, v99, v100
	v_max3_f32 v129, v129, v83, v84
	v_max3_f32 v128, v128, v101, v102
	v_max3_f32 v129, v129, v85, v86
	v_max3_f32 v128, v128, v103, v104
	v_max3_f32 v129, v129, v87, v88
	v_max3_f32 v128, v128, v105, v106
	v_max3_f32 v129, v129, v89, v90
	v_max3_f32 v128, v128, v107, v108
	v_max3_f32 v129, v129, v91, v92
	v_max3_f32 v128, v128, v109, v110
	v_max3_f32 v129, v129, v93, v94
	v_max3_f32 v128, v128, v129, v111
	v_max_f32_e32 v128, v128, v95
	v_cmp_lt_f32_e32 vcc, s96, v128
	s_cbranch_vccz .LBB0_629
	v_mov_b32_e32 v129, v128
	s_nop 1
	v_permlane32_swap_b32_e32 v128, v129
	v_max_f32_e32 v128, v128, v129
	v_max_f32_e32 v64, v128, v128
	v_max_f32_e32 v64, 0, v64
	v_exp_f32_e64 v66, -v64
	v_pk_add_f32 v[96:97], v[96:97], v[64:65] op_sel_hi:[1,0] neg_lo:[0,1] neg_hi:[0,1]
	v_pk_add_f32 v[98:99], v[98:99], v[64:65] op_sel_hi:[1,0] neg_lo:[0,1] neg_hi:[0,1]
	v_pk_add_f32 v[100:101], v[100:101], v[64:65] op_sel_hi:[1,0] neg_lo:[0,1] neg_hi:[0,1]
	v_pk_add_f32 v[102:103], v[102:103], v[64:65] op_sel_hi:[1,0] neg_lo:[0,1] neg_hi:[0,1]
	v_pk_add_f32 v[104:105], v[104:105], v[64:65] op_sel_hi:[1,0] neg_lo:[0,1] neg_hi:[0,1]
	v_pk_add_f32 v[106:107], v[106:107], v[64:65] op_sel_hi:[1,0] neg_lo:[0,1] neg_hi:[0,1]
	v_pk_add_f32 v[108:109], v[108:109], v[64:65] op_sel_hi:[1,0] neg_lo:[0,1] neg_hi:[0,1]
	v_pk_add_f32 v[110:111], v[110:111], v[64:65] op_sel_hi:[1,0] neg_lo:[0,1] neg_hi:[0,1]
	v_mov_b32_e32 v65, v66
	v_sub_f32_e32 v95, v95, v64
	v_sub_f32_e32 v94, v94, v64
	v_sub_f32_e32 v93, v93, v64
	v_sub_f32_e32 v92, v92, v64
	v_sub_f32_e32 v91, v91, v64
	v_sub_f32_e32 v90, v90, v64
	v_sub_f32_e32 v89, v89, v64
	v_sub_f32_e32 v88, v88, v64
	v_sub_f32_e32 v87, v87, v64
	v_sub_f32_e32 v86, v86, v64
	v_sub_f32_e32 v85, v85, v64
	v_sub_f32_e32 v84, v84, v64
	v_sub_f32_e32 v83, v83, v64
	v_sub_f32_e32 v82, v82, v64
	v_sub_f32_e32 v81, v81, v64
	v_sub_f32_e32 v80, v80, v64
	v_pk_mul_f32 v[62:63], v[62:63], v[66:67] op_sel_hi:[1,0]
	v_pk_mul_f32 v[60:61], v[60:61], v[66:67] op_sel_hi:[1,0]
	v_pk_mul_f32 v[58:59], v[58:59], v[66:67] op_sel_hi:[1,0]
	v_pk_mul_f32 v[56:57], v[56:57], v[66:67] op_sel_hi:[1,0]
	v_pk_mul_f32 v[54:55], v[54:55], v[66:67] op_sel_hi:[1,0]
	v_pk_mul_f32 v[52:53], v[52:53], v[66:67] op_sel_hi:[1,0]
	v_pk_mul_f32 v[50:51], v[50:51], v[66:67] op_sel_hi:[1,0]
	v_pk_mul_f32 v[48:49], v[48:49], v[66:67] op_sel_hi:[1,0]
	v_pk_mul_f32 v[14:15], v[14:15], v[66:67] op_sel_hi:[1,0]
	v_pk_mul_f32 v[12:13], v[12:13], v[66:67] op_sel_hi:[1,0]
	v_pk_mul_f32 v[10:11], v[10:11], v[66:67] op_sel_hi:[1,0]
	v_pk_mul_f32 v[8:9], v[8:9], v[66:67] op_sel_hi:[1,0]
	v_pk_mul_f32 v[6:7], v[6:7], v[66:67] op_sel_hi:[1,0]
	v_pk_mul_f32 v[4:5], v[4:5], v[66:67] op_sel_hi:[1,0]
	v_pk_mul_f32 v[2:3], v[2:3], v[66:67] op_sel_hi:[1,0]
	v_pk_mul_f32 v[0:1], v[0:1], v[66:67] op_sel_hi:[1,0]
	v_pk_mul_f32 v[46:47], v[46:47], v[66:67] op_sel_hi:[1,0]
	v_pk_mul_f32 v[44:45], v[44:45], v[66:67] op_sel_hi:[1,0]
	v_pk_mul_f32 v[42:43], v[42:43], v[66:67] op_sel_hi:[1,0]
	v_pk_mul_f32 v[40:41], v[40:41], v[66:67] op_sel_hi:[1,0]
	v_pk_mul_f32 v[38:39], v[38:39], v[66:67] op_sel_hi:[1,0]
	v_pk_mul_f32 v[36:37], v[36:37], v[66:67] op_sel_hi:[1,0]
	v_pk_mul_f32 v[34:35], v[34:35], v[66:67] op_sel_hi:[1,0]
	v_pk_mul_f32 v[32:33], v[32:33], v[66:67] op_sel_hi:[1,0]
	v_pk_mul_f32 v[30:31], v[30:31], v[66:67] op_sel_hi:[1,0]
	v_pk_mul_f32 v[28:29], v[28:29], v[66:67] op_sel_hi:[1,0]
	v_pk_mul_f32 v[26:27], v[26:27], v[66:67] op_sel_hi:[1,0]
	v_pk_mul_f32 v[24:25], v[24:25], v[66:67] op_sel_hi:[1,0]
	v_pk_mul_f32 v[22:23], v[22:23], v[66:67] op_sel_hi:[1,0]
	v_pk_mul_f32 v[20:21], v[20:21], v[66:67] op_sel_hi:[1,0]
	v_pk_mul_f32 v[18:19], v[18:19], v[66:67] op_sel_hi:[1,0]
	v_pk_mul_f32 v[16:17], v[16:17], v[66:67] op_sel_hi:[1,0]
	v_pk_add_f32 v[66:67], v[156:157], v[64:65]
	v_pk_mul_f32 v[64:65], v[156:157], v[64:65]
	s_nop 0
	v_mov_b32_e32 v67, v65
	v_sub_f32_e32 v64, v252, v66
	v_mov_b64_e32 v[156:157], v[66:67]
	v_mov_b32_e32 v65, v64
	v_mov_b32_e32 v66, v64
	v_mov_b32_e32 v67, v64
	v_mov_b32_e32 v68, v64
	v_mov_b32_e32 v69, v64
	v_mov_b32_e32 v70, v64
	v_mov_b32_e32 v71, v64
	v_mov_b32_e32 v72, v64
	v_mov_b32_e32 v73, v64
	v_mov_b32_e32 v74, v64
	v_mov_b32_e32 v75, v64
	v_mov_b32_e32 v76, v64
	v_mov_b32_e32 v77, v64
	v_mov_b32_e32 v78, v64
	v_mov_b32_e32 v79, v64

.LBB0_638:
	s_cmpk_eq_i32 s20, 0xfc0
	s_cbranch_scc1 .LBB0_649

.LBB0_645:
	s_waitcnt lgkmcnt(7)
	v_mfma_f32_32x32x16_bf16 v[48:63], v[128:131], v[170:173], v[48:63]
	v_add_f32_e32 v96, v97, v96
	v_add_f32_e32 v96, v98, v96
	v_add_f32_e32 v80, v81, v80
	v_add_f32_e32 v96, v99, v96
	s_waitcnt lgkmcnt(5)
	v_mfma_f32_32x32x16_bf16 v[0:15], v[136:139], v[170:173], v[0:15]
	s_add_i32 s4, s44, 0x9000
	s_cmp_lg_u32 s44, 0x12000
	s_cselect_b32 s44, s4, 0
	s_add_i32 s4, s45, 1
	v_add_f32_e32 v80, v82, v80
	v_add_f32_e32 v96, v100, v96
	v_add_f32_e32 v80, v83, v80
	v_add_f32_e32 v96, v101, v96
	v_mfma_f32_32x32x16_bf16 v[48:63], v[132:135], v[178:181], v[48:63]
	v_add_f32_e32 v80, v84, v80
	v_add_f32_e32 v96, v102, v96
	v_add_f32_e32 v80, v85, v80
	v_add_f32_e32 v96, v103, v96
	s_waitcnt lgkmcnt(4)
	v_mfma_f32_32x32x16_bf16 v[0:15], v[140:143], v[178:181], v[0:15]
	s_cmp_lg_u32 s45, 2
	s_cselect_b32 s45, s4, 0
	s_add_i32 s33, s33, 1
	s_add_u32 s10, s10, 0x60000
	s_addc_u32 s11, s11, 0
	v_add_f32_e32 v80, v86, v80
	v_add_f32_e32 v96, v104, v96
	v_add_f32_e32 v80, v87, v80
	v_add_f32_e32 v96, v105, v96
	s_waitcnt lgkmcnt(3)
	v_mfma_f32_32x32x16_bf16 v[32:47], v[182:185], v[170:173], v[32:47]
	v_add_f32_e32 v80, v88, v80
	v_add_f32_e32 v96, v106, v96
	v_add_f32_e32 v80, v89, v80
	v_add_f32_e32 v96, v107, v96
	s_waitcnt lgkmcnt(1)
	v_mfma_f32_32x32x16_bf16 v[16:31], v[190:193], v[170:173], v[16:31]
	s_add_i32 s20, s20, 64
	v_add_f32_e32 v80, v90, v80
	v_add_f32_e32 v96, v108, v96
	v_add_f32_e32 v80, v91, v80
	v_add_f32_e32 v96, v109, v96
	v_mfma_f32_32x32x16_bf16 v[32:47], v[186:189], v[178:181], v[32:47]
	v_add_f32_e32 v80, v92, v80
	v_add_f32_e32 v96, v110, v96
	v_add_f32_e32 v80, v93, v80
	v_add_f32_e32 v96, v111, v96
	s_waitcnt lgkmcnt(0)
	v_mfma_f32_32x32x16_bf16 v[16:31], v[194:197], v[178:181], v[16:31]
	v_add_f32_e32 v80, v94, v80
	v_add_f32_e32 v96, v157, v96
	v_add_f32_e32 v80, v95, v80
	v_add_f32_e32 v157, v96, v80
	s_mov_b64 s[60:61], -1
	s_and_b64 vcc, exec, s[50:51]
	s_cbranch_vccz .LBB0_647
	s_waitcnt vmcnt(0) lgkmcnt(0)
	s_barrier
	s_mov_b64 s[60:61], 0

.LBB0_683:
	v_add3_u32 v165, s57, v143, v163
	ds_read_b128 v[190:193], v165 offset:18432
	ds_read_b128 v[194:197], v165 offset:18448
	ds_read_b128 v[128:131], v165 offset:23040
	ds_read_b128 v[132:135], v165 offset:23056
	ds_read_b128 v[136:139], v165 offset:27648
	ds_read_b128 v[166:169], v165 offset:27664
	ds_read_b128 v[170:173], v165 offset:32256
	ds_read_b128 v[178:181], v165 offset:32272
	v_exp_f32_e32 v96, v96
	v_exp_f32_e32 v97, v97
	v_exp_f32_e32 v98, v98
	v_exp_f32_e32 v99, v99
	v_exp_f32_e32 v100, v100
	v_add_f32_e32 v198, v97, v96
	v_exp_f32_e32 v101, v101
	v_add_f32_e32 v198, v98, v198
	v_exp_f32_e32 v102, v102
	v_add_f32_e32 v198, v99, v198
	v_exp_f32_e32 v103, v103
	v_add_f32_e32 v198, v100, v198
	v_exp_f32_e32 v104, v104
	v_add_f32_e32 v198, v101, v198
	v_exp_f32_e32 v105, v105
	v_add_f32_e32 v198, v102, v198
	v_exp_f32_e32 v106, v106
	v_add_f32_e32 v198, v103, v198
	v_exp_f32_e32 v107, v107
	v_add_f32_e32 v198, v104, v198
	v_exp_f32_e32 v108, v108
	v_add_f32_e32 v198, v105, v198
	v_exp_f32_e32 v109, v109
	v_add_f32_e32 v198, v106, v198
	v_exp_f32_e32 v110, v110
	v_add_f32_e32 v198, v107, v198
	v_exp_f32_e32 v111, v111
	v_add_f32_e32 v198, v108, v198
	v_add_f32_e32 v198, v109, v198
	v_add_f32_e32 v198, v110, v198
	v_add_f32_e32 v198, v111, v198
	v_add_f32_e32 v157, v157, v198
	v_cvt_pk_bf16_f32 v96, v96, v97
	v_cvt_pk_bf16_f32 v97, v98, v99
	v_cvt_pk_bf16_f32 v98, v100, v101
	v_cvt_pk_bf16_f32 v99, v102, v103
	v_cvt_pk_bf16_f32 v100, v104, v105
	v_cvt_pk_bf16_f32 v101, v106, v107
	v_cvt_pk_bf16_f32 v102, v108, v109
	v_cvt_pk_bf16_f32 v103, v110, v111
	s_waitcnt lgkmcnt(7)
	v_mfma_f32_32x32x16_bf16 v[48:63], v[190:193], v[96:99], v[48:63]
	v_exp_f32_e32 v174, v80
	v_exp_f32_e32 v175, v81
	v_exp_f32_e32 v182, v82
	v_exp_f32_e32 v183, v83
	v_add_f32_e32 v80, v175, v174
	v_add_f32_e32 v80, v182, v80
	s_waitcnt lgkmcnt(5)
	v_mfma_f32_32x32x16_bf16 v[0:15], v[128:131], v[96:99], v[0:15]
	v_add_f32_e32 v80, v183, v80
	v_mfma_f32_32x32x16_bf16 v[48:63], v[194:197], v[100:103], v[48:63]
	v_exp_f32_e32 v128, v84
	v_exp_f32_e32 v129, v85
	v_exp_f32_e32 v130, v86
	v_exp_f32_e32 v131, v87
	v_add_f32_e32 v80, v128, v80
	v_add_f32_e32 v80, v129, v80
	v_add_f32_e32 v80, v130, v80
	s_waitcnt lgkmcnt(4)
	v_mfma_f32_32x32x16_bf16 v[0:15], v[132:135], v[100:103], v[0:15]
	v_add_f32_e32 v184, v131, v80
	ds_read_b128 v[80:83], v165 offset:18496
	ds_read_b128 v[84:87], v165 offset:18512
	ds_read_b128 v[104:107], v165 offset:23104
	ds_read_b128 v[108:111], v165 offset:23120
	s_waitcnt lgkmcnt(7)
	v_mfma_f32_32x32x16_bf16 v[32:47], v[136:139], v[96:99], v[32:47]
	v_exp_f32_e32 v132, v88
	v_exp_f32_e32 v133, v89
	v_exp_f32_e32 v134, v90
	v_exp_f32_e32 v135, v91
	v_add_f32_e32 v88, v132, v184
	v_add_f32_e32 v88, v133, v88
	v_add_f32_e32 v88, v134, v88
	s_waitcnt lgkmcnt(5)
	v_mfma_f32_32x32x16_bf16 v[16:31], v[170:173], v[96:99], v[16:31]
	v_add_f32_e32 v88, v135, v88
	v_exp_f32_e32 v96, v92
	v_mfma_f32_32x32x16_bf16 v[32:47], v[166:169], v[100:103], v[32:47]
	v_exp_f32_e32 v97, v93
	v_exp_f32_e32 v98, v94
	v_exp_f32_e32 v95, v95
	v_add_f32_e32 v88, v96, v88
	v_add_f32_e32 v88, v97, v88
	v_add_f32_e32 v88, v98, v88
	v_add_f32_e32 v88, v95, v88
	s_waitcnt lgkmcnt(4)
	v_mfma_f32_32x32x16_bf16 v[16:31], v[178:181], v[100:103], v[16:31]
	v_add_f32_e32 v157, v157, v88
	v_cvt_pk_bf16_f32 v88, v174, v175
	v_cvt_pk_bf16_f32 v89, v182, v183
	v_cvt_pk_bf16_f32 v90, v128, v129
	v_cvt_pk_bf16_f32 v91, v130, v131
	v_cvt_pk_bf16_f32 v92, v132, v133
	v_cvt_pk_bf16_f32 v93, v134, v135
	v_cvt_pk_bf16_f32 v94, v96, v97
	v_cvt_pk_bf16_f32 v95, v98, v95
	ds_read_b128 v[96:99], v165 offset:27712
	ds_read_b128 v[100:103], v165 offset:27728
	ds_read_b128 v[128:131], v165 offset:32320
	ds_read_b128 v[132:135], v165 offset:32336
	s_waitcnt lgkmcnt(7)
	v_mfma_f32_32x32x16_bf16 v[48:63], v[80:83], v[88:91], v[48:63]
	s_waitcnt lgkmcnt(5)
	v_mfma_f32_32x32x16_bf16 v[0:15], v[104:107], v[88:91], v[0:15]
	s_add_i32 s4, s9, 0x9000
	s_cmp_lg_u32 s9, 0x12000
	s_cselect_b32 s9, s4, 0
	s_add_i32 s4, s56, 1
	v_mfma_f32_32x32x16_bf16 v[48:63], v[84:87], v[92:95], v[48:63]
	s_waitcnt lgkmcnt(4)
	v_mfma_f32_32x32x16_bf16 v[0:15], v[108:111], v[92:95], v[0:15]
	s_cmp_lg_u32 s56, 2
	s_cselect_b32 s56, s4, 0
	s_add_i32 s8, s8, 1
	s_add_u32 s10, s10, 0x60000
	s_addc_u32 s11, s11, 0
	s_waitcnt lgkmcnt(3)
	v_mfma_f32_32x32x16_bf16 v[32:47], v[96:99], v[88:91], v[32:47]
	s_waitcnt lgkmcnt(1)
	v_mfma_f32_32x32x16_bf16 v[16:31], v[128:131], v[88:91], v[16:31]
	s_add_i32 s58, s58, 64
	v_mfma_f32_32x32x16_bf16 v[32:47], v[100:103], v[92:95], v[32:47]
	s_waitcnt lgkmcnt(0)
	v_mfma_f32_32x32x16_bf16 v[16:31], v[132:135], v[92:95], v[16:31]
	s_cmpk_lg_i32 s58, 0x7c0
	s_waitcnt lgkmcnt(0)
	s_barrier
	s_cbranch_scc0 .LBB0_694

.LBB0_699:
	s_cmpk_eq_i32 s20, 0x7c0
	s_cbranch_scc1 .LBB0_710

.LBB0_706:
	s_waitcnt lgkmcnt(7)
	v_mfma_f32_32x32x16_bf16 v[48:63], v[128:131], v[170:173], v[48:63]
	v_add_f32_e32 v96, v97, v96
	v_add_f32_e32 v96, v98, v96
	v_add_f32_e32 v80, v81, v80
	v_add_f32_e32 v96, v99, v96
	s_waitcnt lgkmcnt(5)
	v_mfma_f32_32x32x16_bf16 v[0:15], v[136:139], v[170:173], v[0:15]
	s_add_i32 s4, s44, 0x9000
	s_cmp_lg_u32 s44, 0x12000
	s_cselect_b32 s44, s4, 0
	v_add_f32_e32 v80, v82, v80
	v_add_f32_e32 v96, v100, v96
	v_add_f32_e32 v80, v83, v80
	v_add_f32_e32 v96, v101, v96
	v_mfma_f32_32x32x16_bf16 v[48:63], v[132:135], v[178:181], v[48:63]
	v_add_f32_e32 v80, v84, v80
	v_add_f32_e32 v96, v102, v96
	v_add_f32_e32 v80, v85, v80
	v_add_f32_e32 v96, v103, v96
	s_waitcnt lgkmcnt(4)
	v_mfma_f32_32x32x16_bf16 v[0:15], v[140:143], v[178:181], v[0:15]
	s_add_i32 s4, s45, 1
	s_cmp_lg_u32 s45, 2
	s_cselect_b32 s45, s4, 0
	v_add_f32_e32 v80, v86, v80
	v_add_f32_e32 v96, v104, v96
	v_add_f32_e32 v80, v87, v80
	v_add_f32_e32 v96, v105, v96
	s_waitcnt lgkmcnt(3)
	v_mfma_f32_32x32x16_bf16 v[32:47], v[182:185], v[170:173], v[32:47]
	v_add_f32_e32 v80, v88, v80
	v_add_f32_e32 v96, v106, v96
	v_add_f32_e32 v80, v89, v80
	v_add_f32_e32 v96, v107, v96
	s_waitcnt lgkmcnt(1)
	v_mfma_f32_32x32x16_bf16 v[16:31], v[190:193], v[170:173], v[16:31]
	s_add_i32 s33, s33, 1
	s_add_i32 s20, s20, 64
	v_add_f32_e32 v80, v90, v80
	v_add_f32_e32 v96, v108, v96
	v_add_f32_e32 v80, v91, v80
	v_add_f32_e32 v96, v109, v96
	v_mfma_f32_32x32x16_bf16 v[32:47], v[186:189], v[178:181], v[32:47]
	v_add_f32_e32 v80, v92, v80
	v_add_f32_e32 v96, v110, v96
	v_add_f32_e32 v80, v93, v80
	v_add_f32_e32 v96, v111, v96
	s_waitcnt lgkmcnt(0)
	v_mfma_f32_32x32x16_bf16 v[16:31], v[194:197], v[178:181], v[16:31]
	v_add_f32_e32 v80, v94, v80
	v_add_f32_e32 v96, v157, v96
	v_add_f32_e32 v80, v95, v80
	v_add_f32_e32 v157, v96, v80
	s_mov_b64 s[62:63], -1
	s_and_b64 vcc, exec, s[60:61]
	s_cbranch_vccz .LBB0_708
	s_waitcnt vmcnt(0) lgkmcnt(0)
	s_barrier
	s_mov_b64 s[62:63], 0
